# attention: one lgkmcnt wait per P.V slice / per QK^T fragment pair (fewer s_waitcnt), otherwise as the previous best
# baseline (speedup 1.0000x reference)
; #define SBAR() __builtin_amdgcn_sched_barrier(0)
; #define SLOAD(i, k0) do { const char* vt_ = (const char*)Vh + (size_t)(k0) * 256; const char* kt_ = (const char*)Kh + (size_t)(k0) * 128; \
;     sr_[i].vs0 = *reinterpret_cast<const bf16x8*>(vt_ + voff0); sr_[i].vs1 = *reinterpret_cast<const bf16x8*>(vt_ + 32 * 256 + voff0); \
;     sr_[i].ks0 = *reinterpret_cast<const bf16x8*>(kt_ + koff0); } while (0)
; #define SBAR() __builtin_amdgcn_sched_barrier(0)
; template <int KS> __device__ __forceinline__ void pv_ks(f32x16* o, int vb, bf16x8 pa) {
;     const s16x4 l0 = tr_read<v_rd_off(0, KS, 0)>(vb), h0 = tr_read<v_rd_off(0, KS, 1)>(vb), l1 = tr_read<v_rd_off(1, KS, 0)>(vb), h1 = tr_read<v_rd_off(1, KS, 1)>(vb);
;     const s16x4 l2 = tr_read<v_rd_off(2, KS, 0)>(vb), h2 = tr_read<v_rd_off(2, KS, 1)>(vb), l3 = tr_read<v_rd_off(3, KS, 0)>(vb), h3 = tr_read<v_rd_off(3, KS, 1)>(vb);
;     asm volatile("s_waitcnt lgkmcnt(0)" ::: "memory"); SBAR();
;     ...
;     o[0] = __builtin_amdgcn_mfma_f32_32x32x16_bf16(pa, PK(l0, h0), o[0], 0, 0, 0);
;     o[1] = __builtin_amdgcn_mfma_f32_32x32x16_bf16(pa, PK(l1, h1), o[1], 0, 0, 0);
;     o[2] = __builtin_amdgcn_mfma_f32_32x32x16_bf16(pa, PK(l2, h2), o[2], 0, 0, 0);
;     o[3] = __builtin_amdgcn_mfma_f32_32x32x16_bf16(pa, PK(l3, h3), o[3], 0, 0, 0);
;     ...
; }
; __device__ __forceinline__ void attn_unit(const bf16* __restrict__ Qb, const bf16* __restrict__ Kh, const bf16* __restrict__ Vh, bf16* __restrict__ Ob, int seq, char* lds) {
;     ...
;     for (int j = 1; j + 1 < NT; j += 2) {
;         SBAR(); qkt(pB0, pB1, K_lds + SHM_K, qr, r32, hi); pv_ks<0>(o, vb0, pa0); SBAR();
;         softHalf(pA1, l_reg, pa2, pa3); SBAR();
;         SLOAD(SO, (j + 1) * KVBLK); SBAR();
;         pv_ks<1>(o, vb0, pa1); pv_ks<2>(o, vb0, pa2); pv_ks<3>(o, vb0, pa3); SBAR();
;         softHalf(pB0, l_reg, pa0, pa1); SBAR();
.LBB0_531:
	ds_read_b128 v[82:85], v157 offset:40960
	ds_read_b128 v[86:89], v157 offset:45056
	ds_read_b128 v[164:167], v159 offset:40960
	ds_read_b128 v[168:171], v159 offset:45056
	ds_read_b128 v[188:191], v162 offset:40960
	ds_read_b128 v[230:233], v162 offset:45056
	ds_read_b128 v[234:237], v163 offset:40960
	ds_read_b128 v[242:245], v163 offset:45056
	v_exp_f32_e32 v66, v66
	v_exp_f32_e32 v67, v67
	v_exp_f32_e32 v68, v68
	s_waitcnt lgkmcnt(7)
	v_mfma_f32_32x32x16_bf16 v[98:113], v[82:85], v[126:129], 0
	v_exp_f32_e32 v69, v69
	v_exp_f32_e32 v70, v70
	v_exp_f32_e32 v71, v71
	s_waitcnt lgkmcnt(6)
	v_mfma_f32_32x32x16_bf16 v[82:97], v[86:89], v[126:129], 0
	v_add_f32_e32 v179, v67, v66
	v_exp_f32_e32 v72, v72
	v_add_f32_e32 v179, v68, v179
	s_waitcnt lgkmcnt(4)
	v_mfma_f32_32x32x16_bf16 v[98:113], v[164:167], v[122:125], v[98:113]
	v_exp_f32_e32 v73, v73
	v_add_f32_e32 v179, v69, v179
	v_exp_f32_e32 v74, v74
	v_mfma_f32_32x32x16_bf16 v[82:97], v[168:171], v[122:125], v[82:97]
	ds_read_b64_tr_b16 v[172:173], v156 offset:0
	ds_read_b64_tr_b16 v[174:175], v156 offset:0x800
	ds_read_b64_tr_b16 v[164:165], v156 offset:0x200
	ds_read_b64_tr_b16 v[166:167], v156 offset:0xa00
	ds_read_b64_tr_b16 v[180:181], v156 offset:0x400
	ds_read_b64_tr_b16 v[182:183], v156 offset:0xc00
	ds_read_b64_tr_b16 v[184:185], v156 offset:0x600
	ds_read_b64_tr_b16 v[186:187], v156 offset:0xe00
	v_add_f32_e32 v179, v70, v179
	v_exp_f32_e32 v75, v75
	v_add_f32_e32 v179, v71, v179
	s_waitcnt lgkmcnt(10)
	v_mfma_f32_32x32x16_bf16 v[98:113], v[188:191], v[118:121], v[98:113]
	v_exp_f32_e32 v76, v76
	v_add_f32_e32 v179, v72, v179
	v_exp_f32_e32 v77, v77
	v_mfma_f32_32x32x16_bf16 v[82:97], v[230:233], v[118:121], v[82:97]
	v_add_f32_e32 v179, v73, v179
	v_exp_f32_e32 v78, v78
	v_add_f32_e32 v179, v74, v179
	s_waitcnt lgkmcnt(8)
	v_mfma_f32_32x32x16_bf16 v[98:113], v[234:237], v[114:117], v[98:113]
	v_exp_f32_e32 v79, v79
	v_add_f32_e32 v179, v75, v179
	v_exp_f32_e32 v80, v80
	v_mfma_f32_32x32x16_bf16 v[82:97], v[242:245], v[114:117], v[82:97]
	v_add_f32_e32 v179, v76, v179
	v_exp_f32_e32 v81, v81
	v_add_f32_e32 v179, v77, v179
	v_add_f32_e32 v179, v78, v179
	s_waitcnt lgkmcnt(0)
	v_mfma_f32_32x32x16_bf16 v[2:17], v[134:137], v[172:175], v[2:17]
	ds_read_b64_tr_b16 v[188:189], v156 offset:0x1000
	ds_read_b64_tr_b16 v[190:191], v156 offset:0x1800
	ds_read_b64_tr_b16 v[230:231], v156 offset:0x1200
	ds_read_b64_tr_b16 v[232:233], v156 offset:0x1a00
	ds_read_b64_tr_b16 v[234:235], v156 offset:0x1400
	ds_read_b64_tr_b16 v[236:237], v156 offset:0x1c00
	ds_read_b64_tr_b16 v[242:243], v156 offset:0x1600
	ds_read_b64_tr_b16 v[244:245], v156 offset:0x1e00
	v_add_f32_e32 v179, v79, v179
	v_add_f32_e32 v179, v80, v179
	v_add_f32_e32 v179, v81, v179
	v_cvt_pk_bf16_f32 v66, v66, v67
	v_mfma_f32_32x32x16_bf16 v[18:33], v[134:137], v[164:167], v[18:33]
	v_cvt_pk_bf16_f32 v67, v68, v69
	v_cvt_pk_bf16_f32 v68, v70, v71
	v_cvt_pk_bf16_f32 v69, v72, v73
	v_cvt_pk_bf16_f32 v70, v74, v75
	v_mfma_f32_32x32x16_bf16 v[34:49], v[134:137], v[180:183], v[34:49]
	v_cvt_pk_bf16_f32 v71, v76, v77
	v_cvt_pk_bf16_f32 v72, v78, v79
	v_cvt_pk_bf16_f32 v73, v80, v81
	v_add_f32_e32 v221, v139, v179
	v_mfma_f32_32x32x16_bf16 v[50:65], v[134:137], v[184:187], v[50:65]
	global_load_dwordx4 v[74:77], v148, s[80:81]
	global_load_dwordx4 v[78:81], v148, s[82:83]
	global_load_dwordx4 v[164:167], v146, s[84:85]
	v_exp_f32_e32 v220, v98
	v_exp_f32_e32 v177, v99
	s_waitcnt lgkmcnt(0)
	v_mfma_f32_32x32x16_bf16 v[2:17], v[130:133], v[188:191], v[2:17]
	ds_read_b64_tr_b16 v[168:169], v156 offset:0x2000
	ds_read_b64_tr_b16 v[170:171], v156 offset:0x2800
	ds_read_b64_tr_b16 v[172:173], v156 offset:0x2200
	ds_read_b64_tr_b16 v[174:175], v156 offset:0x2a00
	ds_read_b64_tr_b16 v[180:181], v156 offset:0x2400
	ds_read_b64_tr_b16 v[182:183], v156 offset:0x2c00
	ds_read_b64_tr_b16 v[184:185], v156 offset:0x2600
	ds_read_b64_tr_b16 v[186:187], v156 offset:0x2e00
	v_exp_f32_e32 v193, v100
	v_exp_f32_e32 v195, v101
	v_exp_f32_e32 v197, v102
	v_mfma_f32_32x32x16_bf16 v[18:33], v[130:133], v[230:233], v[18:33]
	v_exp_f32_e32 v199, v103
	v_exp_f32_e32 v201, v104
	v_mfma_f32_32x32x16_bf16 v[34:49], v[130:133], v[234:237], v[34:49]
	v_exp_f32_e32 v203, v105
	v_cvt_pk_bf16_f32 v222, v220, v177
	v_cvt_pk_bf16_f32 v223, v193, v195
	v_mfma_f32_32x32x16_bf16 v[50:65], v[130:133], v[242:245], v[50:65]
	v_cvt_pk_bf16_f32 v224, v197, v199
	v_cvt_pk_bf16_f32 v225, v201, v203
	v_exp_f32_e32 v205, v106
	s_waitcnt lgkmcnt(0)
	v_mfma_f32_32x32x16_bf16 v[2:17], v[66:69], v[168:171], v[2:17]
	ds_read_b64_tr_b16 v[188:189], v156 offset:0x3000
	ds_read_b64_tr_b16 v[190:191], v156 offset:0x3800
	ds_read_b64_tr_b16 v[230:231], v156 offset:0x3200
	ds_read_b64_tr_b16 v[232:233], v156 offset:0x3a00
	ds_read_b64_tr_b16 v[234:235], v156 offset:0x3400
	ds_read_b64_tr_b16 v[236:237], v156 offset:0x3c00
	ds_read_b64_tr_b16 v[242:243], v156 offset:0x3600
	ds_read_b64_tr_b16 v[244:245], v156 offset:0x3e00
	v_exp_f32_e32 v207, v107
	v_exp_f32_e32 v209, v108
	v_exp_f32_e32 v211, v109
	v_mfma_f32_32x32x16_bf16 v[18:33], v[66:69], v[172:175], v[18:33]
	v_exp_f32_e32 v213, v110
	v_exp_f32_e32 v215, v111
	v_mfma_f32_32x32x16_bf16 v[34:49], v[66:69], v[180:183], v[34:49]
	v_exp_f32_e32 v217, v112
	v_exp_f32_e32 v219, v113
	v_add_f32_e32 v238, v177, v220
	v_mfma_f32_32x32x16_bf16 v[50:65], v[66:69], v[184:187], v[50:65]
	s_waitcnt lgkmcnt(0)
	s_barrier
; #define SBAR() __builtin_amdgcn_sched_barrier(0)
; #define SLOAD(i, k0) do { const char* vt_ = (const char*)Vh + (size_t)(k0) * 256; const char* kt_ = (const char*)Kh + (size_t)(k0) * 128; \
;     sr_[i].vs0 = *reinterpret_cast<const bf16x8*>(vt_ + voff0); sr_[i].vs1 = *reinterpret_cast<const bf16x8*>(vt_ + 32 * 256 + voff0); \
;     sr_[i].ks0 = *reinterpret_cast<const bf16x8*>(kt_ + koff0); } while (0)
; #define SWRITE(b, i) do { *(bf16x8*)(V_lds + (b) * SHM_V + vst0) = sr_[i].vs0; *(bf16x8*)(V_lds + (b) * SHM_V + vst1) = sr_[i].vs1; \
;     *(bf16x8*)(K_lds + (b) * SHM_K + kst) = sr_[i].ks0; } while (0)
; #define SWAIT() asm volatile("s_waitcnt vmcnt(0)" ::: "memory")
; #define SBAR() __builtin_amdgcn_sched_barrier(0)
; __device__ __forceinline__ void attn_unit(const bf16* __restrict__ Qb, const bf16* __restrict__ Kh, const bf16* __restrict__ Vh, bf16* __restrict__ Ob, int seq, char* lds) {
;     ...
;         __syncthreads(); SWAIT(); SWRITE(0, SE);
;         __syncthreads();
;         SBAR(); qkt(pA0, pA1, K_lds, qr, r32, hi); pv_ks<0>(o, vb0 + SHM_V, pa0); SBAR();
;         softHalf(pB1, l_reg, pa2, pa3); SBAR();
;         SLOAD(SE, (j + 2) * KVBLK); SBAR();
;         pv_ks<1>(o, vb0 + SHM_V, pa1); pv_ks<2>(o, vb0 + SHM_V, pa2); pv_ks<3>(o, vb0 + SHM_V, pa3); SBAR();
;         softHalf(pA0, l_reg, pa0, pa1); SBAR();
;         __syncthreads(); SWAIT(); SWRITE(1, SO);
	s_waitcnt vmcnt(0)
	s_waitcnt vmcnt(2)
	ds_write_b128 v160, v[74:77]
	s_waitcnt vmcnt(1)
	ds_write_b128 v161, v[78:81]
	s_waitcnt vmcnt(0)
	ds_write_b128 v158, v[164:167] offset:32768
	v_add_f32_e32 v238, v193, v238
	v_add_f32_e32 v238, v195, v238
	v_add_f32_e32 v238, v197, v238
	v_add_f32_e32 v238, v199, v238
	v_add_f32_e32 v238, v201, v238
	v_mfma_f32_32x32x16_bf16 v[2:17], v[70:73], v[188:191], v[2:17]
	v_add_f32_e32 v238, v203, v238
	v_add_f32_e32 v238, v205, v238
	v_add_f32_e32 v238, v207, v238
	v_add_f32_e32 v238, v209, v238
	v_add_f32_e32 v238, v211, v238
	v_mfma_f32_32x32x16_bf16 v[18:33], v[70:73], v[230:233], v[18:33]
	v_add_f32_e32 v238, v213, v238
	v_add_f32_e32 v238, v215, v238
	v_add_f32_e32 v238, v217, v238
	v_add_f32_e32 v238, v219, v238
	v_add_f32_e32 v238, v221, v238
	v_mfma_f32_32x32x16_bf16 v[34:49], v[70:73], v[234:237], v[34:49]
	v_cvt_pk_bf16_f32 v226, v205, v207
	v_cvt_pk_bf16_f32 v227, v209, v211
	v_cvt_pk_bf16_f32 v228, v213, v215
	v_cvt_pk_bf16_f32 v229, v217, v219
	v_mfma_f32_32x32x16_bf16 v[50:65], v[70:73], v[242:245], v[50:65]
	s_waitcnt lgkmcnt(0)
	s_barrier
	ds_read_b128 v[66:69], v157 offset:32768
	ds_read_b128 v[70:73], v157 offset:36864
	ds_read_b128 v[164:167], v159 offset:32768
	ds_read_b128 v[172:175], v159 offset:36864
	ds_read_b128 v[230:233], v162 offset:32768
	ds_read_b128 v[234:237], v162 offset:36864
	ds_read_b128 v[168:171], v163 offset:32768
	ds_read_b128 v[242:245], v163 offset:36864
	v_exp_f32_e32 v176, v82
	v_exp_f32_e32 v192, v83
	v_exp_f32_e32 v194, v84
	s_waitcnt lgkmcnt(7)
	v_mfma_f32_32x32x16_bf16 v[98:113], v[66:69], v[126:129], 0
	v_exp_f32_e32 v196, v85
	v_exp_f32_e32 v198, v86
	v_exp_f32_e32 v200, v87
	s_waitcnt lgkmcnt(6)
	v_mfma_f32_32x32x16_bf16 v[66:81], v[70:73], v[126:129], 0
	v_add_f32_e32 v82, v192, v176
	v_exp_f32_e32 v202, v88
	v_add_f32_e32 v82, v194, v82
	s_waitcnt lgkmcnt(4)
	v_mfma_f32_32x32x16_bf16 v[98:113], v[164:167], v[122:125], v[98:113]
	v_exp_f32_e32 v204, v89
	v_add_f32_e32 v82, v196, v82
	v_exp_f32_e32 v206, v90
	v_mfma_f32_32x32x16_bf16 v[66:81], v[172:175], v[122:125], v[66:81]
	ds_read_b64_tr_b16 v[180:181], v141 offset:0
	ds_read_b64_tr_b16 v[182:183], v141 offset:0x800
	ds_read_b64_tr_b16 v[164:165], v141 offset:0x200
	ds_read_b64_tr_b16 v[166:167], v141 offset:0xa00
	ds_read_b64_tr_b16 v[184:185], v141 offset:0x400
	ds_read_b64_tr_b16 v[186:187], v141 offset:0xc00
	ds_read_b64_tr_b16 v[188:189], v141 offset:0x600
	ds_read_b64_tr_b16 v[190:191], v141 offset:0xe00
	v_add_f32_e32 v82, v198, v82
	v_exp_f32_e32 v208, v91
	v_add_f32_e32 v82, v200, v82
	s_waitcnt lgkmcnt(10)
	v_mfma_f32_32x32x16_bf16 v[98:113], v[230:233], v[118:121], v[98:113]
	v_exp_f32_e32 v210, v92
	v_add_f32_e32 v82, v202, v82
	v_exp_f32_e32 v212, v93
	v_mfma_f32_32x32x16_bf16 v[66:81], v[234:237], v[118:121], v[66:81]
	v_add_f32_e32 v82, v204, v82
	v_exp_f32_e32 v214, v94
	v_add_f32_e32 v82, v206, v82
	s_waitcnt lgkmcnt(8)
	v_mfma_f32_32x32x16_bf16 v[98:113], v[168:171], v[114:117], v[98:113]
	v_exp_f32_e32 v216, v95
	v_add_f32_e32 v82, v208, v82
	v_exp_f32_e32 v218, v96
	v_mfma_f32_32x32x16_bf16 v[66:81], v[242:245], v[114:117], v[66:81]
	v_add_f32_e32 v82, v210, v82
	v_exp_f32_e32 v220, v97
	v_add_f32_e32 v82, v212, v82
	v_add_f32_e32 v82, v214, v82
	s_waitcnt lgkmcnt(0)
	v_mfma_f32_32x32x16_bf16 v[2:17], v[222:225], v[180:183], v[2:17]
	ds_read_b64_tr_b16 v[230:231], v141 offset:0x1000
	ds_read_b64_tr_b16 v[232:233], v141 offset:0x1800
	ds_read_b64_tr_b16 v[234:235], v141 offset:0x1200
	ds_read_b64_tr_b16 v[236:237], v141 offset:0x1a00
	ds_read_b64_tr_b16 v[168:169], v141 offset:0x1400
	ds_read_b64_tr_b16 v[170:171], v141 offset:0x1c00
	ds_read_b64_tr_b16 v[172:173], v141 offset:0x1600
	ds_read_b64_tr_b16 v[174:175], v141 offset:0x1e00
	v_add_f32_e32 v82, v216, v82
	v_add_f32_e32 v82, v218, v82
	v_add_f32_e32 v82, v220, v82
	v_add_f32_e32 v139, v82, v238
	v_cvt_pk_bf16_f32 v82, v176, v192
	v_mfma_f32_32x32x16_bf16 v[18:33], v[222:225], v[164:167], v[18:33]
	v_cvt_pk_bf16_f32 v83, v194, v196
	v_cvt_pk_bf16_f32 v84, v198, v200
	v_cvt_pk_bf16_f32 v85, v202, v204
	v_mfma_f32_32x32x16_bf16 v[34:49], v[222:225], v[184:187], v[34:49]
	v_cvt_pk_bf16_f32 v86, v206, v208
	v_cvt_pk_bf16_f32 v87, v210, v212
	v_cvt_pk_bf16_f32 v88, v214, v216
	v_cvt_pk_bf16_f32 v89, v218, v220
	v_mfma_f32_32x32x16_bf16 v[50:65], v[222:225], v[188:191], v[50:65]
	global_load_dwordx4 v[90:93], v148, s[86:87]
	global_load_dwordx4 v[94:97], v148, s[88:89]
	global_load_dwordx4 v[164:167], v146, s[90:91]
	v_exp_f32_e32 v239, v98
	v_exp_f32_e32 v241, v99
	s_waitcnt lgkmcnt(0)
	v_mfma_f32_32x32x16_bf16 v[2:17], v[226:229], v[230:233], v[2:17]
	ds_read_b64_tr_b16 v[180:181], v141 offset:0x2000
	ds_read_b64_tr_b16 v[182:183], v141 offset:0x2800
	ds_read_b64_tr_b16 v[184:185], v141 offset:0x2200
	ds_read_b64_tr_b16 v[186:187], v141 offset:0x2a00
	ds_read_b64_tr_b16 v[188:189], v141 offset:0x2400
	ds_read_b64_tr_b16 v[190:191], v141 offset:0x2c00
	ds_read_b64_tr_b16 v[222:223], v141 offset:0x2600
	ds_read_b64_tr_b16 v[224:225], v141 offset:0x2e00
	v_exp_f32_e32 v242, v100
	v_exp_f32_e32 v243, v101
	v_exp_f32_e32 v244, v102
	v_mfma_f32_32x32x16_bf16 v[18:33], v[226:229], v[234:237], v[18:33]
	v_exp_f32_e32 v98, v106
	v_exp_f32_e32 v245, v103
	v_mfma_f32_32x32x16_bf16 v[34:49], v[226:229], v[168:171], v[34:49]
	v_add_f32_e32 v106, v241, v239
	v_exp_f32_e32 v246, v104
	v_add_f32_e32 v106, v242, v106
	v_mfma_f32_32x32x16_bf16 v[50:65], v[226:229], v[172:175], v[50:65]
	v_exp_f32_e32 v247, v105
	v_add_f32_e32 v106, v243, v106
	v_add_f32_e32 v106, v244, v106
	v_exp_f32_e32 v99, v107
	s_waitcnt lgkmcnt(0)
	v_mfma_f32_32x32x16_bf16 v[2:17], v[82:85], v[180:183], v[2:17]
	ds_read_b64_tr_b16 v[230:231], v141 offset:0x3000
	ds_read_b64_tr_b16 v[232:233], v141 offset:0x3800
	ds_read_b64_tr_b16 v[234:235], v141 offset:0x3200
	ds_read_b64_tr_b16 v[236:237], v141 offset:0x3a00
	ds_read_b64_tr_b16 v[168:169], v141 offset:0x3400
	ds_read_b64_tr_b16 v[170:171], v141 offset:0x3c00
	ds_read_b64_tr_b16 v[172:173], v141 offset:0x3600
	ds_read_b64_tr_b16 v[174:175], v141 offset:0x3e00
	v_add_f32_e32 v106, v245, v106
	v_exp_f32_e32 v100, v108
	v_add_f32_e32 v106, v246, v106
	v_mfma_f32_32x32x16_bf16 v[18:33], v[82:85], v[184:187], v[18:33]
	v_exp_f32_e32 v101, v109
	v_add_f32_e32 v106, v247, v106
	v_exp_f32_e32 v102, v110
	v_add_f32_e32 v106, v98, v106
	v_mfma_f32_32x32x16_bf16 v[34:49], v[82:85], v[188:191], v[34:49]
	v_exp_f32_e32 v103, v111
	v_add_f32_e32 v106, v99, v106
	v_exp_f32_e32 v104, v112
	v_mfma_f32_32x32x16_bf16 v[50:65], v[82:85], v[222:225], v[50:65]
	s_waitcnt lgkmcnt(0)
	s_barrier
; #define SBAR() __builtin_amdgcn_sched_barrier(0)
; #define SWRITE(b, i) do { *(bf16x8*)(V_lds + (b) * SHM_V + vst0) = sr_[i].vs0; *(bf16x8*)(V_lds + (b) * SHM_V + vst1) = sr_[i].vs1; \
;     *(bf16x8*)(K_lds + (b) * SHM_K + kst) = sr_[i].ks0; } while (0)
; #define SWAIT() asm volatile("s_waitcnt vmcnt(0)" ::: "memory")
; #define SBAR() __builtin_amdgcn_sched_barrier(0)
; __device__ __forceinline__ void attn_unit(const bf16* __restrict__ Qb, const bf16* __restrict__ Kh, const bf16* __restrict__ Vh, bf16* __restrict__ Ob, int seq, char* lds) {
;     ...
;         __syncthreads(); SWAIT(); SWRITE(1, SO);
;         __syncthreads();
;     }
;     SBAR(); qkt(pB0, pB1, K_lds + SHM_K, qr, r32, hi); pv_ks<0>(o, vb0, pa0); SBAR();
;     softHalf(pA1, l_reg, pa2, pa3); SBAR();
;     pv_ks<1>(o, vb0, pa1); pv_ks<2>(o, vb0, pa2); pv_ks<3>(o, vb0, pa3); SBAR();
;     softHalf(pB0, l_reg, pa0, pa1); SBAR();
;     pv_ks<0>(o, vb0 + SHM_V, pa0); SBAR();
	s_waitcnt vmcnt(0)
	s_add_i32 s10, s10, 2
	v_add_u32_e32 v146, 0x4000, v146
	s_cmp_gt_u32 s10, 32
	v_add_u32_e32 v148, 0x8000, v148
	s_waitcnt vmcnt(2)
	ds_write_b128 v160, v[90:93] offset:16384
	s_waitcnt vmcnt(1)
	ds_write_b128 v161, v[94:97] offset:16384
	s_waitcnt vmcnt(0)
	ds_write_b128 v158, v[164:167] offset:40960
	v_add_f32_e32 v106, v100, v106
	v_exp_f32_e32 v105, v113
	v_add_f32_e32 v106, v101, v106
	v_mfma_f32_32x32x16_bf16 v[2:17], v[86:89], v[230:233], v[2:17]
	v_add_f32_e32 v106, v102, v106
	v_add_f32_e32 v106, v103, v106
	v_add_f32_e32 v106, v104, v106
	v_add_f32_e32 v106, v105, v106
	v_cvt_pk_bf16_f32 v134, v239, v241
	v_mfma_f32_32x32x16_bf16 v[18:33], v[86:89], v[234:237], v[18:33]
	v_cvt_pk_bf16_f32 v135, v242, v243
	v_cvt_pk_bf16_f32 v136, v244, v245
	v_cvt_pk_bf16_f32 v137, v246, v247
	v_cvt_pk_bf16_f32 v130, v98, v99
	v_mfma_f32_32x32x16_bf16 v[34:49], v[86:89], v[168:171], v[34:49]
	v_cvt_pk_bf16_f32 v131, v100, v101
	v_cvt_pk_bf16_f32 v132, v102, v103
	v_cvt_pk_bf16_f32 v133, v104, v105
	v_add_f32_e32 v139, v139, v106
	v_mfma_f32_32x32x16_bf16 v[50:65], v[86:89], v[172:175], v[50:65]
	s_waitcnt lgkmcnt(0)
	s_barrier
	s_cbranch_scc0 .LBB0_531
	v_and_b32_e32 v82, 0x3fffffc0, v143
	v_lshl_add_u32 v143, v82, 2, 0
	ds_read_b128 v[82:85], v157 offset:40960
	ds_read_b128 v[86:89], v157 offset:45056
	s_waitcnt lgkmcnt(1)
	v_mfma_f32_32x32x16_bf16 v[98:113], v[82:85], v[126:129], 0
	s_waitcnt lgkmcnt(0)
	v_mfma_f32_32x32x16_bf16 v[82:97], v[86:89], v[126:129], 0
	ds_read_b128 v[126:129], v159 offset:40960
	ds_read_b128 v[146:149], v159 offset:45056
	s_waitcnt lgkmcnt(1)
	v_mfma_f32_32x32x16_bf16 v[98:113], v[126:129], v[122:125], v[98:113]
	s_waitcnt lgkmcnt(0)
	v_mfma_f32_32x32x16_bf16 v[82:97], v[146:149], v[122:125], v[82:97]
	ds_read_b128 v[122:125], v162 offset:40960
	ds_read_b128 v[126:129], v162 offset:45056
	s_waitcnt lgkmcnt(1)
	v_mfma_f32_32x32x16_bf16 v[98:113], v[122:125], v[118:121], v[98:113]
	s_waitcnt lgkmcnt(0)
	v_mfma_f32_32x32x16_bf16 v[82:97], v[126:129], v[118:121], v[82:97]
	ds_read_b128 v[118:121], v163 offset:40960
	ds_read_b128 v[122:125], v163 offset:45056
	ds_read_b64_tr_b16 v[126:127], v156 offset:0
	ds_read_b64_tr_b16 v[128:129], v156 offset:0x800
	s_waitcnt lgkmcnt(1)
	v_mfma_f32_32x32x16_bf16 v[98:113], v[118:121], v[114:117], v[98:113]
	ds_read_b64_tr_b16 v[118:119], v156 offset:0x200
	ds_read_b64_tr_b16 v[120:121], v156 offset:0xa00
	ds_read_b64_tr_b16 v[146:147], v156 offset:0x400
	ds_read_b64_tr_b16 v[148:149], v156 offset:0xc00
	ds_read_b64_tr_b16 v[158:159], v156 offset:0x600
	ds_read_b64_tr_b16 v[160:161], v156 offset:0xe00
	s_waitcnt lgkmcnt(0)
	s_waitcnt lgkmcnt(0)
	v_mfma_f32_32x32x16_bf16 v[82:97], v[122:125], v[114:117], v[82:97]
	v_mfma_f32_32x32x16_bf16 v[2:17], v[134:137], v[126:129], v[2:17]
	v_mfma_f32_32x32x16_bf16 v[18:33], v[134:137], v[118:121], v[18:33]
	v_mfma_f32_32x32x16_bf16 v[34:49], v[134:137], v[146:149], v[34:49]
	v_mfma_f32_32x32x16_bf16 v[50:65], v[134:137], v[158:161], v[50:65]
	v_exp_f32_e32 v66, v66
	v_exp_f32_e32 v67, v67
	v_exp_f32_e32 v68, v68
	v_exp_f32_e32 v69, v69
	v_exp_f32_e32 v70, v70
	v_add_f32_e32 v114, 0, v66
	v_exp_f32_e32 v71, v71
	v_add_f32_e32 v114, v67, v114
	v_exp_f32_e32 v72, v72
	v_add_f32_e32 v114, v68, v114
	v_exp_f32_e32 v73, v73
	v_add_f32_e32 v114, v69, v114
	v_exp_f32_e32 v74, v74
	v_add_f32_e32 v114, v70, v114
	v_exp_f32_e32 v75, v75
	v_add_f32_e32 v114, v71, v114
	v_exp_f32_e32 v76, v76
	v_add_f32_e32 v114, v72, v114
	v_exp_f32_e32 v77, v77
	v_add_f32_e32 v114, v73, v114
	v_exp_f32_e32 v78, v78
	v_add_f32_e32 v114, v74, v114
	v_exp_f32_e32 v79, v79
	v_add_f32_e32 v114, v75, v114
	v_exp_f32_e32 v80, v80
	v_add_f32_e32 v114, v76, v114
	v_exp_f32_e32 v81, v81
	v_add_f32_e32 v114, v77, v114
	v_add_f32_e32 v114, v78, v114
	v_add_f32_e32 v114, v79, v114
	v_add_f32_e32 v114, v80, v114
	v_cvt_pk_bf16_f32 v66, v66, v67
	v_cvt_pk_bf16_f32 v67, v68, v69
	v_cvt_pk_bf16_f32 v68, v70, v71
	v_cvt_pk_bf16_f32 v69, v72, v73
	v_add_f32_e32 v114, v81, v114
	v_cvt_pk_bf16_f32 v70, v74, v75
	v_cvt_pk_bf16_f32 v71, v76, v77
	v_cvt_pk_bf16_f32 v72, v78, v79
	v_cvt_pk_bf16_f32 v73, v80, v81
	v_add_f32_e32 v126, v139, v114
	ds_read_b64_tr_b16 v[74:75], v156 offset:0x1000
	ds_read_b64_tr_b16 v[76:77], v156 offset:0x1800
	ds_read_b64_tr_b16 v[78:79], v156 offset:0x1200
	ds_read_b64_tr_b16 v[80:81], v156 offset:0x1a00
	ds_read_b64_tr_b16 v[114:115], v156 offset:0x1400
	ds_read_b64_tr_b16 v[116:117], v156 offset:0x1c00
	ds_read_b64_tr_b16 v[118:119], v156 offset:0x1600
	ds_read_b64_tr_b16 v[120:121], v156 offset:0x1e00
	s_waitcnt lgkmcnt(0)
	s_nop 0
	v_mfma_f32_32x32x16_bf16 v[2:17], v[130:133], v[74:77], v[2:17]
	ds_read_b64_tr_b16 v[74:75], v156 offset:0x2000
	ds_read_b64_tr_b16 v[76:77], v156 offset:0x2800
	v_mfma_f32_32x32x16_bf16 v[18:33], v[130:133], v[78:81], v[18:33]
	ds_read_b64_tr_b16 v[78:79], v156 offset:0x2200
	ds_read_b64_tr_b16 v[80:81], v156 offset:0x2a00
	v_mfma_f32_32x32x16_bf16 v[34:49], v[130:133], v[114:117], v[34:49]
	ds_read_b64_tr_b16 v[114:115], v156 offset:0x2400
	ds_read_b64_tr_b16 v[116:117], v156 offset:0x2c00
	ds_read_b64_tr_b16 v[122:123], v156 offset:0x2600
	ds_read_b64_tr_b16 v[124:125], v156 offset:0x2e00
	s_waitcnt lgkmcnt(0)
	v_mfma_f32_32x32x16_bf16 v[50:65], v[130:133], v[118:121], v[50:65]
	v_mfma_f32_32x32x16_bf16 v[2:17], v[66:69], v[74:77], v[2:17]
	ds_read_b64_tr_b16 v[74:75], v156 offset:0x3000
	ds_read_b64_tr_b16 v[76:77], v156 offset:0x3800
	v_mfma_f32_32x32x16_bf16 v[18:33], v[66:69], v[78:81], v[18:33]
	ds_read_b64_tr_b16 v[78:79], v156 offset:0x3200
	ds_read_b64_tr_b16 v[80:81], v156 offset:0x3a00
	v_mfma_f32_32x32x16_bf16 v[34:49], v[66:69], v[114:117], v[34:49]
	ds_read_b64_tr_b16 v[114:115], v156 offset:0x3400
	ds_read_b64_tr_b16 v[116:117], v156 offset:0x3c00
	ds_read_b64_tr_b16 v[118:119], v156 offset:0x3600
	ds_read_b64_tr_b16 v[120:121], v156 offset:0x3e00
	s_waitcnt lgkmcnt(0)
; #define SBAR() __builtin_amdgcn_sched_barrier(0)
; #define SBAR() __builtin_amdgcn_sched_barrier(0)
; __device__ __forceinline__ void attn_unit(const bf16* __restrict__ Qb, const bf16* __restrict__ Kh, const bf16* __restrict__ Vh, bf16* __restrict__ Ob, int seq, char* lds) {
;     ...
;     pv_ks<0>(o, vb0 + SHM_V, pa0); SBAR();
;     softHalf(pB1, l_reg, pa2, pa3); SBAR();
;     pv_ks<1>(o, vb0 + SHM_V, pa1); pv_ks<2>(o, vb0 + SHM_V, pa2); pv_ks<3>(o, vb0 + SHM_V, pa3);
;     { auto rr = __builtin_amdgcn_permlane32_swap(__float_as_uint(l_reg), __float_as_uint(l_reg), false, false); l_reg = __uint_as_float(rr[0]) + __uint_as_float(rr[1]); }
;     if (hi == 0) wsf[r32] = l_reg; asm volatile("s_waitcnt lgkmcnt(0)" ::: "memory");
	v_mfma_f32_32x32x16_bf16 v[50:65], v[66:69], v[122:125], v[50:65]
	v_mfma_f32_32x32x16_bf16 v[2:17], v[70:73], v[74:77], v[2:17]
	v_mfma_f32_32x32x16_bf16 v[18:33], v[70:73], v[78:81], v[18:33]
	v_mfma_f32_32x32x16_bf16 v[34:49], v[70:73], v[114:117], v[34:49]
	v_mfma_f32_32x32x16_bf16 v[50:65], v[70:73], v[118:121], v[50:65]
	v_exp_f32_e32 v66, v98
	v_exp_f32_e32 v67, v99
	v_exp_f32_e32 v68, v100
	v_exp_f32_e32 v69, v101
	v_exp_f32_e32 v70, v102
	v_add_f32_e32 v98, 0, v66
	v_exp_f32_e32 v71, v103
	v_add_f32_e32 v98, v67, v98
	v_exp_f32_e32 v72, v104
	v_add_f32_e32 v98, v68, v98
	v_exp_f32_e32 v73, v105
	v_add_f32_e32 v98, v69, v98
	v_exp_f32_e32 v74, v106
	v_add_f32_e32 v98, v70, v98
	v_exp_f32_e32 v75, v107
	v_add_f32_e32 v98, v71, v98
	v_exp_f32_e32 v76, v108
	v_add_f32_e32 v98, v72, v98
	v_exp_f32_e32 v77, v109
	v_add_f32_e32 v98, v73, v98
	v_exp_f32_e32 v78, v110
	v_add_f32_e32 v98, v74, v98
	v_exp_f32_e32 v79, v111
	v_add_f32_e32 v98, v75, v98
	v_exp_f32_e32 v80, v112
	v_add_f32_e32 v98, v76, v98
	v_exp_f32_e32 v81, v113
	v_add_f32_e32 v98, v77, v98
	v_add_f32_e32 v98, v78, v98
	v_add_f32_e32 v98, v79, v98
	v_add_f32_e32 v98, v80, v98
	v_cvt_pk_bf16_f32 v66, v66, v67
	v_cvt_pk_bf16_f32 v67, v68, v69
	v_cvt_pk_bf16_f32 v68, v70, v71
	v_cvt_pk_bf16_f32 v69, v72, v73
	v_add_f32_e32 v98, v81, v98
	v_cvt_pk_bf16_f32 v70, v74, v75
	v_cvt_pk_bf16_f32 v71, v76, v77
	v_cvt_pk_bf16_f32 v72, v78, v79
	v_cvt_pk_bf16_f32 v73, v80, v81
	v_add_f32_e32 v106, v126, v98
	ds_read_b64_tr_b16 v[74:75], v141 offset:0
	ds_read_b64_tr_b16 v[76:77], v141 offset:0x800
	ds_read_b64_tr_b16 v[78:79], v141 offset:0x200
	ds_read_b64_tr_b16 v[80:81], v141 offset:0xa00
	ds_read_b64_tr_b16 v[98:99], v141 offset:0x400
	ds_read_b64_tr_b16 v[100:101], v141 offset:0xc00
	ds_read_b64_tr_b16 v[102:103], v141 offset:0x600
	ds_read_b64_tr_b16 v[104:105], v141 offset:0xe00
	s_waitcnt lgkmcnt(0)
	s_nop 0
	v_mfma_f32_32x32x16_bf16 v[2:17], v[66:69], v[74:77], v[2:17]
	v_mfma_f32_32x32x16_bf16 v[18:33], v[66:69], v[78:81], v[18:33]
	v_mfma_f32_32x32x16_bf16 v[34:49], v[66:69], v[98:101], v[34:49]
	v_mfma_f32_32x32x16_bf16 v[50:65], v[66:69], v[102:105], v[50:65]
	v_exp_f32_e32 v67, v82
	v_exp_f32_e32 v68, v83
	v_exp_f32_e32 v69, v84
	v_exp_f32_e32 v75, v85
	v_exp_f32_e32 v76, v86
	v_add_f32_e32 v66, 0, v67
	v_exp_f32_e32 v77, v87
	v_add_f32_e32 v66, v68, v66
	v_exp_f32_e32 v78, v88
	v_add_f32_e32 v66, v69, v66
	v_exp_f32_e32 v79, v89
	v_add_f32_e32 v66, v75, v66
	v_exp_f32_e32 v80, v90
	v_add_f32_e32 v66, v76, v66
	v_exp_f32_e32 v81, v91
	v_add_f32_e32 v66, v77, v66
	v_exp_f32_e32 v82, v92
	v_add_f32_e32 v66, v78, v66
	v_exp_f32_e32 v83, v93
	v_add_f32_e32 v66, v79, v66
	v_exp_f32_e32 v84, v94
	v_add_f32_e32 v66, v80, v66
	v_exp_f32_e32 v85, v95
	v_add_f32_e32 v66, v81, v66
	v_exp_f32_e32 v86, v96
	v_add_f32_e32 v66, v82, v66
	v_exp_f32_e32 v87, v97
	v_add_f32_e32 v66, v83, v66
	v_add_f32_e32 v66, v84, v66
	v_add_f32_e32 v66, v85, v66
	v_add_f32_e32 v66, v86, v66
	v_add_f32_e32 v66, v87, v66
	v_add_f32_e32 v66, v66, v106
	v_cvt_pk_bf16_f32 v74, v67, v68
	v_cvt_pk_bf16_f32 v75, v69, v75
	v_cvt_pk_bf16_f32 v76, v76, v77
	v_cvt_pk_bf16_f32 v77, v78, v79
	v_cvt_pk_bf16_f32 v78, v80, v81
	v_cvt_pk_bf16_f32 v79, v82, v83
	v_cvt_pk_bf16_f32 v80, v84, v85
	v_cvt_pk_bf16_f32 v81, v86, v87
	s_nop 0
	ds_read_b64_tr_b16 v[82:83], v141 offset:0x1000
	ds_read_b64_tr_b16 v[84:85], v141 offset:0x1800
	ds_read_b64_tr_b16 v[86:87], v141 offset:0x1200
	ds_read_b64_tr_b16 v[88:89], v141 offset:0x1a00
	ds_read_b64_tr_b16 v[90:91], v141 offset:0x1400
	ds_read_b64_tr_b16 v[92:93], v141 offset:0x1c00
	ds_read_b64_tr_b16 v[94:95], v141 offset:0x1600
	ds_read_b64_tr_b16 v[96:97], v141 offset:0x1e00
	s_waitcnt lgkmcnt(0)
	s_nop 0
	v_mfma_f32_32x32x16_bf16 v[2:17], v[70:73], v[82:85], v[2:17]
	ds_read_b64_tr_b16 v[82:83], v141 offset:0x2000
	ds_read_b64_tr_b16 v[84:85], v141 offset:0x2800
	v_mfma_f32_32x32x16_bf16 v[18:33], v[70:73], v[86:89], v[18:33]
	ds_read_b64_tr_b16 v[86:87], v141 offset:0x2200
	ds_read_b64_tr_b16 v[88:89], v141 offset:0x2a00
	v_mfma_f32_32x32x16_bf16 v[34:49], v[70:73], v[90:93], v[34:49]
	ds_read_b64_tr_b16 v[90:91], v141 offset:0x2400
	ds_read_b64_tr_b16 v[92:93], v141 offset:0x2c00
	ds_read_b64_tr_b16 v[98:99], v141 offset:0x2600
	ds_read_b64_tr_b16 v[100:101], v141 offset:0x2e00
	s_waitcnt lgkmcnt(0)
	v_mfma_f32_32x32x16_bf16 v[50:65], v[70:73], v[94:97], v[50:65]
	ds_read_b64_tr_b16 v[68:69], v141 offset:0x3000
	ds_read_b64_tr_b16 v[70:71], v141 offset:0x3800
	v_mfma_f32_32x32x16_bf16 v[2:17], v[74:77], v[82:85], v[2:17]
	ds_read_b64_tr_b16 v[82:83], v141 offset:0x3200
	ds_read_b64_tr_b16 v[84:85], v141 offset:0x3a00
	v_mfma_f32_32x32x16_bf16 v[18:33], v[74:77], v[86:89], v[18:33]
	ds_read_b64_tr_b16 v[86:87], v141 offset:0x3400
	ds_read_b64_tr_b16 v[88:89], v141 offset:0x3c00
	v_mfma_f32_32x32x16_bf16 v[34:49], v[74:77], v[90:93], v[34:49]
	ds_read_b64_tr_b16 v[90:91], v141 offset:0x3600
	ds_read_b64_tr_b16 v[92:93], v141 offset:0x3e00
	s_waitcnt lgkmcnt(0)
	v_mfma_f32_32x32x16_bf16 v[50:65], v[74:77], v[98:101], v[50:65]
	v_mfma_f32_32x32x16_bf16 v[2:17], v[78:81], v[68:71], v[2:17]
	v_mov_b32_e32 v67, v66
	s_nop 1
	v_permlane32_swap_b32_e32 v66, v67
	v_cmp_gt_u32_e32 vcc, 32, v145
	v_mfma_f32_32x32x16_bf16 v[18:33], v[78:81], v[82:85], v[18:33]
	v_mfma_f32_32x32x16_bf16 v[34:49], v[78:81], v[86:89], v[34:49]
	v_mfma_f32_32x32x16_bf16 v[50:65], v[78:81], v[90:93], v[50:65]
	s_and_saveexec_b64 s[10:11], vcc
	s_cbranch_execz .LBB0_529
	v_add_f32_e32 v66, v66, v67
	v_lshl_add_u32 v67, v153, 2, v143
	ds_write_b32 v67, v66 offset:49152
	s_branch .LBB0_529
